# phase 0: workgroups that also run the adaLN GEMV take 21 weight-conversion tiles, the others 27 (was 26 each)
# speedup vs baseline: 1.0675x; 1.0036x over previous
; DI void phase0(const Params& p, char* lds0) {
;     ...
;     for (int item0 = bid; item0 < 48; item0 += G) {
;       const int item = item0 * 2 + vb;
;     ...
;   {
;     float* tl = (float*)lds;
;     const int n_in = 16 * 40, n_out = 16 * 16, n_gu = 32 * 256, n_d = 32 * 128;
;     const int total = n_in + n_out + n_gu + n_d;
;     for (int it0 = bid; it0 < total / 2; it0 += G) {
;       const int it = it0 * 2 + vb;
;       if (it < n_in) {
;         int kt = it / 40, nt = it % 40;
;         transpose_tile(p.w_in, (bfr*)(ws + WS_WIN), 1024, 2560, kt * 64, nt * 64, tl, tid);
;       } else if (it < n_in + n_out) {
;         int i2 = it - n_in; int kt = i2 >> 4, nt = i2 & 15;
;         transpose_tile(p.w_out, (bfr*)(ws + WS_WOUT), 1024, 1024, kt * 64, nt * 64, tl, tid);
;       } else if (it < n_in + n_out + n_gu) {
;         int i2 = it - n_in - n_out; int e = i2 >> 8, r = i2 & 255; int kt = r >> 4, nt = r & 15;
;         transpose_tile(p.w_gu + (size_t)e * 1024 * 1024, (bfr*)(ws + WS_WGU) + (size_t)e * 1024 * 1024, 1024, 1024, kt * 64, nt * 64, tl, tid);
;       } else {
;         int i2 = it - n_in - n_out - n_gu; int e = i2 >> 7, r = i2 & 127; int kt = r >> 4, nt = r & 15;
;         transpose_tile(p.w_d + (size_t)e * 512 * 1024, (bfr*)(ws + WS_WD) + (size_t)e * 1024 * 512, 512, 1024, kt * 64, nt * 64, tl, tid);
;       }
;     }
.LBB0_44:
	s_cmpk_gt_i32 s2, 0x19bf
	s_cbranch_scc1 .LBB0_59
	s_mov_b32 s98, s2
	s_mov_b32 s99, s72
	s_movk_i32 s100, 0x19c0
	s_cmp_eq_u32 s72, 0x100
	s_cbranch_scc0 .Lcv_map_done
	s_cmp_lt_u32 s2, 48
	s_cbranch_scc1 .Lcv_map_gemv
	s_sub_u32 s98, s2, 48
	s_movk_i32 s99, 0xd0
	s_movk_i32 s100, 0x15f0
	s_branch .Lcv_map_done
.Lcv_map_gemv:
	s_add_u32 s98, s2, 0x15f0
	s_movk_i32 s99, 48
.Lcv_map_done:
	v_lshlrev_b32_e32 v3, 2, v2
	v_lshrrev_b32_e32 v18, 4, v34
	v_and_b32_e32 v16, 60, v3
	v_mul_u32_u24_e32 v4, 0x104, v18
	v_lshlrev_b32_e32 v14, 2, v16
	v_add3_u32 v19, v33, v4, v14
	v_lshlrev_b32_e32 v4, 3, v2
	v_lshlrev_b32_e32 v2, 4, v2
	v_mov_b32_e32 v3, 0
	v_and_b32_e32 v27, 56, v4
	v_and_b32_e32 v2, 48, v2
	v_lshrrev_b32_e32 v26, 3, v34
	v_mul_u32_u24_e32 v6, 0x41, v27
	s_waitcnt lgkmcnt(0)
	v_lshl_add_u64 v[10:11], s[12:13], 0, v[2:3]
	s_mov_b64 s[4:5], 0x4894400
	v_lshl_add_u64 v[4:5], v[10:11], 0, s[4:5]
	v_lshlrev_b32_e32 v2, 2, v26
	v_lshlrev_b32_e32 v6, 2, v6
	s_mov_b64 s[4:5], 0x894400
	v_add3_u32 v28, v33, v2, v6
	v_add3_u32 v29, v33, v6, v2
	v_lshl_add_u64 v[6:7], v[10:11], 0, s[4:5]
	s_mov_b64 s[4:5], 0x694400
	v_lshl_add_u64 v[8:9], v[10:11], 0, s[4:5]
	s_mov_b64 s[4:5], 0x194400
	s_load_dwordx2 s[8:9], s[74:75], 0x98
	s_load_dwordx2 s[10:11], s[74:75], 0x38
	v_lshl_add_u64 v[10:11], v[10:11], 0, s[4:5]
	s_load_dwordx4 s[4:7], s[74:75], 0xc8
	v_mov_b32_e32 v15, v3
	v_lshl_add_u32 v31, s98, 1, v1
	v_lshlrev_b32_e32 v1, 2, v1
	v_or_b32_e32 v20, 16, v18
	v_add_u32_e32 v21, 0x1040, v19
	v_or_b32_e32 v22, 32, v18
	v_add_u32_e32 v23, 0x2080, v19
	v_or_b32_e32 v24, 48, v18
	v_add_u32_e32 v25, 0x30c0, v19
	v_or_b32_e32 v30, 32, v26
	s_waitcnt lgkmcnt(0)
	v_lshl_add_u64 v[12:13], s[8:9], 0, v[14:15]
	v_lshl_add_u64 v[14:15], s[10:11], 0, v[14:15]
	s_lshl_b32 s3, s99, 1
	v_lshl_add_u32 v1, s98, 3, v1
	s_lshl_b32 s14, s99, 3
	v_lshl_add_u32 v32, s98, 7, v32
	s_lshl_b32 s15, s99, 7
	s_movk_i32 s16, 0x27f
	s_movk_i32 s17, 0x37f
	s_movk_i32 s18, 0x237f
	s_mov_b32 s19, 0x66666667
	s_movk_i32 s20, 0x2800
	s_movk_i32 s21, 0xa00
	v_lshlrev_b32_e32 v16, 2, v16
	v_add_u32_e32 v33, 0x400, v29
	s_mov_b32 s22, s98
	s_branch .LBB0_47
.LBB0_46:
	s_or_b64 exec, exec, s[8:9]
	s_add_i32 s22, s22, s99
	v_add_u32_e32 v31, s3, v31
	v_add_u32_e32 v1, s14, v1
	s_cmp_lt_i32 s22, s100
	v_add_u32_e32 v32, s15, v32
	s_cbranch_scc0 .LBB0_59
